# GEMM epilogues: EpiResid transposes accumulator slabs through per-wave LDS scratch for coalesced f32 residual loads/stores with rolling load window; EpiStore shuffles packed bf16 payload with ds_bperm
# speedup vs baseline: 1.0120x; 1.0120x over previous
;     DI void operator()(const f32x4 (&acc)[2][2][4][2], const Unit& u, int wr, int wc, int fr, int fq) const {
;         const int trow = u.pm * BM; const bool lat = trow < ML;
;         const float* src = lat ? src_l : src_c; float* dst = lat ? dst_l : dst_c;
;         const int rbase = (lat ? trow : trow - ML) + wr * 64 + fr; const int grow = lat ? (trow >> 12) : 16;
;         const float* gp = gate + (size_t)grow * 6144;
;         const int col0 = u.pn * BM + wc * 32 + 8 * fq;
; #pragma unroll
;         for (int bj = 0; bj < 2; ++bj) {
;             const int col = col0 + bj * HALF;
;             const f32x4 g0 = *(const f32x4*)(gp + col), g1 = *(const f32x4*)(gp + col + 4);
; #pragma unroll
;             for (int ai = 0; ai < 2; ++ai)
; #pragma unroll
;                 for (int m = 0; m < 4; ++m) { const size_t off = (size_t)(rbase + ai * HALF + m * 16) * D + col;
;                     const f32x4 x0 = *(const f32x4*)(src + off), x1 = *(const f32x4*)(src + off + 4);
;                     *(f32x4*)(dst + off) = x0 + g0 * acc[ai][bj][m][0]; *(f32x4*)(dst + off + 4) = x1 + g1 * acc[ai][bj][m][1]; }
;         }
;     }
.LBB0_701:
	s_lshl_b32 s12, s75, 8
	s_add_i32 s13, s12, 0xffff0000
	s_cmpk_lt_i32 s75, 0x100
	s_cselect_b32 s12, s12, s13
	s_cselect_b32 s69, s11, s15
	s_cselect_b32 s68, s10, s14
	s_cselect_b32 s27, s19, s3
	s_cselect_b32 s26, s18, s2
	s_min_i32 s34, s75, 0x100
	s_ashr_i32 s34, s34, 4
	s_mul_hi_i32 s35, s34, 0x6000
	s_mulk_i32 s34, 0x6000
	s_add_u32 s34, s79, s34
	s_addc_u32 s35, s80, s35
	v_and_b32_e32 v159, 15, v175
	v_lshrrev_b32_e32 v160, 6, v175
	v_bfe_u32 v161, v177, 3, 2
	v_lshrrev_b32_e32 v162, 5, v177
	v_lshl_add_u32 v163, v161, 4, v159
	v_lshl_add_u32 v154, v160, 2, v162
	v_mul_u32_u24_e32 v154, 0x900, v154
	v_add_u32_e32 v154, 0x21000, v154
	v_lshrrev_b32_e32 v157, 3, v163
	v_and_b32_e32 v158, 7, v163
	v_mul_u32_u24_e32 v155, 0x90, v157
	v_lshl_add_u32 v155, v158, 4, v155
	v_add_u32_e32 v155, v154, v155
	v_mul_u32_u24_e32 v156, 0x90, v159
	v_lshl_add_u32 v156, v161, 5, v156
	v_add_u32_e32 v154, v154, v156
	v_lshl_add_u32 v157, v160, 6, v157
	v_add_u32_e32 v157, s12, v157
	v_lshlrev_b32_e32 v158, 2, v158
	v_lshl_add_u32 v158, v162, 5, v158
	v_lshl_add_u32 v158, s31, 8, v158
	v_lshl_add_u32 v156, v157, 10, v158
	v_lshlrev_b32_e32 v156, 2, v156
	v_lshlrev_b32_e32 v158, 2, v158
	v_add_u32_e32 v157, 0x8000, v156
	global_load_dwordx4 v[128:131], v158, s[34:35]
	global_load_dwordx4 v[132:135], v158, s[34:35] offset:512
	global_load_dwordx4 v[180:183], v156, s[68:69]
	global_load_dwordx4 v[184:187], v156, s[68:69] offset:512
	global_load_dwordx4 v[188:191], v157, s[68:69]
	global_load_dwordx4 v[192:195], v157, s[68:69] offset:512
	s_add_u32 s68, s68, 0x10000
	s_addc_u32 s69, s69, 0
	global_load_dwordx4 v[196:199], v156, s[68:69]
	global_load_dwordx4 v[200:203], v156, s[68:69] offset:512
	global_load_dwordx4 v[204:207], v157, s[68:69]
	global_load_dwordx4 v[214:217], v157, s[68:69] offset:512
	s_add_u32 s68, s68, 0x10000
	s_addc_u32 s69, s69, 0
	global_load_dwordx4 v[218:221], v156, s[68:69]
	global_load_dwordx4 v[222:225], v156, s[68:69] offset:512
	global_load_dwordx4 v[226:229], v157, s[68:69]
	global_load_dwordx4 v[230:233], v157, s[68:69] offset:512
	s_add_u32 s68, s68, 0x10000
	s_addc_u32 s69, s69, 0
	ds_write_b128 v154, v[124:127]
	ds_write_b128 v154, v[120:123] offset:16
	ds_read_b128 v[124:127], v155
	ds_read_b128 v[120:123], v155 offset:1152
	ds_write_b128 v154, v[60:63]
	ds_write_b128 v154, v[56:59] offset:16
	ds_read_b128 v[60:63], v155
	ds_read_b128 v[56:59], v155 offset:1152
	ds_write_b128 v154, v[116:119]
	ds_write_b128 v154, v[112:115] offset:16
	ds_read_b128 v[116:119], v155
	ds_read_b128 v[112:115], v155 offset:1152
	ds_write_b128 v154, v[52:55]
	ds_write_b128 v154, v[48:51] offset:16
	ds_read_b128 v[52:55], v155
	ds_read_b128 v[48:51], v155 offset:1152
	s_waitcnt vmcnt(8) lgkmcnt(8)
	v_pk_fma_f32 v[124:125], v[124:125], v[128:129], v[180:181]
	v_pk_fma_f32 v[126:127], v[126:127], v[130:131], v[182:183]
	v_pk_fma_f32 v[60:61], v[60:61], v[132:133], v[184:185]
	v_pk_fma_f32 v[62:63], v[62:63], v[134:135], v[186:187]
	v_pk_fma_f32 v[120:121], v[120:121], v[128:129], v[188:189]
	v_pk_fma_f32 v[122:123], v[122:123], v[130:131], v[190:191]
	v_pk_fma_f32 v[56:57], v[56:57], v[132:133], v[192:193]
	v_pk_fma_f32 v[58:59], v[58:59], v[134:135], v[194:195]
	global_store_dwordx4 v156, v[124:127], s[26:27]
	global_store_dwordx4 v156, v[60:63], s[26:27] offset:512
	global_store_dwordx4 v157, v[120:123], s[26:27]
	global_store_dwordx4 v157, v[56:59], s[26:27] offset:512
	s_add_u32 s26, s26, 0x10000
	s_addc_u32 s27, s27, 0
	global_load_dwordx4 v[180:183], v156, s[68:69]
	global_load_dwordx4 v[184:187], v156, s[68:69] offset:512
	global_load_dwordx4 v[188:191], v157, s[68:69]
	global_load_dwordx4 v[192:195], v157, s[68:69] offset:512
	s_add_u32 s68, s68, 0x50000
	s_addc_u32 s69, s69, 0
	ds_write_b128 v154, v[108:111]
	ds_write_b128 v154, v[104:107] offset:16
	ds_read_b128 v[108:111], v155
	ds_read_b128 v[104:107], v155 offset:1152
	ds_write_b128 v154, v[44:47]
	ds_write_b128 v154, v[40:43] offset:16
	ds_read_b128 v[44:47], v155
	ds_read_b128 v[40:43], v155 offset:1152
	s_waitcnt vmcnt(12) lgkmcnt(8)
	v_pk_fma_f32 v[116:117], v[116:117], v[128:129], v[196:197]
	v_pk_fma_f32 v[118:119], v[118:119], v[130:131], v[198:199]
	v_pk_fma_f32 v[52:53], v[52:53], v[132:133], v[200:201]
	v_pk_fma_f32 v[54:55], v[54:55], v[134:135], v[202:203]
	v_pk_fma_f32 v[112:113], v[112:113], v[128:129], v[204:205]
	v_pk_fma_f32 v[114:115], v[114:115], v[130:131], v[206:207]
	v_pk_fma_f32 v[48:49], v[48:49], v[132:133], v[214:215]
	v_pk_fma_f32 v[50:51], v[50:51], v[134:135], v[216:217]
	global_store_dwordx4 v156, v[116:119], s[26:27]
	global_store_dwordx4 v156, v[52:55], s[26:27] offset:512
	global_store_dwordx4 v157, v[112:115], s[26:27]
	global_store_dwordx4 v157, v[48:51], s[26:27] offset:512
	s_add_u32 s26, s26, 0x10000
	s_addc_u32 s27, s27, 0
	global_load_dwordx4 v[196:199], v156, s[68:69]
	global_load_dwordx4 v[200:203], v156, s[68:69] offset:512
	global_load_dwordx4 v[204:207], v157, s[68:69]
	global_load_dwordx4 v[214:217], v157, s[68:69] offset:512
	s_add_u32 s68, s68, 0x10000
	s_addc_u32 s69, s69, 0
	ds_write_b128 v154, v[100:103]
	ds_write_b128 v154, v[96:99] offset:16
	ds_read_b128 v[100:103], v155
	ds_read_b128 v[96:99], v155 offset:1152
	ds_write_b128 v154, v[36:39]
	ds_write_b128 v154, v[32:35] offset:16
	ds_read_b128 v[36:39], v155
	ds_read_b128 v[32:35], v155 offset:1152
	s_waitcnt vmcnt(16) lgkmcnt(8)
;     DI void operator()(const f32x4 (&acc)[2][2][4][2], const Unit& u, int wr, int wc, int fr, int fq) const {
;         const int trow = u.pm * BM; const bool lat = trow < ML;
;         const float* src = lat ? src_l : src_c; float* dst = lat ? dst_l : dst_c;
;         const int rbase = (lat ? trow : trow - ML) + wr * 64 + fr; const int grow = lat ? (trow >> 12) : 16;
;         const float* gp = gate + (size_t)grow * 6144;
;         const int col0 = u.pn * BM + wc * 32 + 8 * fq;
; #pragma unroll
;         for (int bj = 0; bj < 2; ++bj) {
;             const int col = col0 + bj * HALF;
;             const f32x4 g0 = *(const f32x4*)(gp + col), g1 = *(const f32x4*)(gp + col + 4);
; #pragma unroll
;             for (int ai = 0; ai < 2; ++ai)
; #pragma unroll
;                 for (int m = 0; m < 4; ++m) { const size_t off = (size_t)(rbase + ai * HALF + m * 16) * D + col;
;                     const f32x4 x0 = *(const f32x4*)(src + off), x1 = *(const f32x4*)(src + off + 4);
;                     *(f32x4*)(dst + off) = x0 + g0 * acc[ai][bj][m][0]; *(f32x4*)(dst + off + 4) = x1 + g1 * acc[ai][bj][m][1]; }
;         }
;     }
	v_pk_fma_f32 v[108:109], v[108:109], v[128:129], v[218:219]
	v_pk_fma_f32 v[110:111], v[110:111], v[130:131], v[220:221]
	v_pk_fma_f32 v[44:45], v[44:45], v[132:133], v[222:223]
	v_pk_fma_f32 v[46:47], v[46:47], v[134:135], v[224:225]
	v_pk_fma_f32 v[104:105], v[104:105], v[128:129], v[226:227]
	v_pk_fma_f32 v[106:107], v[106:107], v[130:131], v[228:229]
	v_pk_fma_f32 v[40:41], v[40:41], v[132:133], v[230:231]
	v_pk_fma_f32 v[42:43], v[42:43], v[134:135], v[232:233]
	global_store_dwordx4 v156, v[108:111], s[26:27]
	global_store_dwordx4 v156, v[44:47], s[26:27] offset:512
	global_store_dwordx4 v157, v[104:107], s[26:27]
	global_store_dwordx4 v157, v[40:43], s[26:27] offset:512
	s_add_u32 s26, s26, 0x10000
	s_addc_u32 s27, s27, 0
	global_load_dwordx4 v[218:221], v156, s[68:69]
	global_load_dwordx4 v[222:225], v156, s[68:69] offset:512
	global_load_dwordx4 v[226:229], v157, s[68:69]
	global_load_dwordx4 v[230:233], v157, s[68:69] offset:512
	s_add_u32 s68, s68, 0x10000
	s_addc_u32 s69, s69, 0
	ds_write_b128 v154, v[92:95]
	ds_write_b128 v154, v[88:91] offset:16
	ds_read_b128 v[92:95], v155
	ds_read_b128 v[88:91], v155 offset:1152
	ds_write_b128 v154, v[28:31]
	ds_write_b128 v154, v[24:27] offset:16
	ds_read_b128 v[28:31], v155
	ds_read_b128 v[24:27], v155 offset:1152
	s_waitcnt vmcnt(16) lgkmcnt(8)
	v_pk_fma_f32 v[100:101], v[100:101], v[128:129], v[180:181]
	v_pk_fma_f32 v[102:103], v[102:103], v[130:131], v[182:183]
	v_pk_fma_f32 v[36:37], v[36:37], v[132:133], v[184:185]
	v_pk_fma_f32 v[38:39], v[38:39], v[134:135], v[186:187]
	v_pk_fma_f32 v[96:97], v[96:97], v[128:129], v[188:189]
	v_pk_fma_f32 v[98:99], v[98:99], v[130:131], v[190:191]
	v_pk_fma_f32 v[32:33], v[32:33], v[132:133], v[192:193]
	v_pk_fma_f32 v[34:35], v[34:35], v[134:135], v[194:195]
	global_store_dwordx4 v156, v[100:103], s[26:27]
	global_store_dwordx4 v156, v[36:39], s[26:27] offset:512
	global_store_dwordx4 v157, v[96:99], s[26:27]
	global_store_dwordx4 v157, v[32:35], s[26:27] offset:512
	s_add_u32 s26, s26, 0x50000
	s_addc_u32 s27, s27, 0
	global_load_dwordx4 v[180:183], v156, s[68:69]
	global_load_dwordx4 v[184:187], v156, s[68:69] offset:512
	global_load_dwordx4 v[188:191], v157, s[68:69]
	global_load_dwordx4 v[192:195], v157, s[68:69] offset:512
	s_add_u32 s68, s68, 0x10000
	s_addc_u32 s69, s69, 0
	ds_write_b128 v154, v[84:87]
	ds_write_b128 v154, v[80:83] offset:16
	ds_read_b128 v[84:87], v155
	ds_read_b128 v[80:83], v155 offset:1152
	ds_write_b128 v154, v[20:23]
	ds_write_b128 v154, v[16:19] offset:16
	ds_read_b128 v[20:23], v155
	ds_read_b128 v[16:19], v155 offset:1152
	s_waitcnt vmcnt(16) lgkmcnt(8)
	v_pk_fma_f32 v[92:93], v[92:93], v[128:129], v[196:197]
	v_pk_fma_f32 v[94:95], v[94:95], v[130:131], v[198:199]
	v_pk_fma_f32 v[28:29], v[28:29], v[132:133], v[200:201]
	v_pk_fma_f32 v[30:31], v[30:31], v[134:135], v[202:203]
	v_pk_fma_f32 v[88:89], v[88:89], v[128:129], v[204:205]
	v_pk_fma_f32 v[90:91], v[90:91], v[130:131], v[206:207]
	v_pk_fma_f32 v[24:25], v[24:25], v[132:133], v[214:215]
	v_pk_fma_f32 v[26:27], v[26:27], v[134:135], v[216:217]
	global_store_dwordx4 v156, v[92:95], s[26:27]
	global_store_dwordx4 v156, v[28:31], s[26:27] offset:512
	global_store_dwordx4 v157, v[88:91], s[26:27]
	global_store_dwordx4 v157, v[24:27], s[26:27] offset:512
	s_add_u32 s26, s26, 0x10000
	s_addc_u32 s27, s27, 0
	global_load_dwordx4 v[196:199], v156, s[68:69]
	global_load_dwordx4 v[200:203], v156, s[68:69] offset:512
	global_load_dwordx4 v[204:207], v157, s[68:69]
	global_load_dwordx4 v[214:217], v157, s[68:69] offset:512
	ds_write_b128 v154, v[76:79]
	ds_write_b128 v154, v[72:75] offset:16
	ds_read_b128 v[76:79], v155
	ds_read_b128 v[72:75], v155 offset:1152
	ds_write_b128 v154, v[12:15]
	ds_write_b128 v154, v[8:11] offset:16
	ds_read_b128 v[12:15], v155
	ds_read_b128 v[8:11], v155 offset:1152
	s_waitcnt vmcnt(16) lgkmcnt(8)
	v_pk_fma_f32 v[84:85], v[84:85], v[128:129], v[218:219]
	v_pk_fma_f32 v[86:87], v[86:87], v[130:131], v[220:221]
	v_pk_fma_f32 v[20:21], v[20:21], v[132:133], v[222:223]
	v_pk_fma_f32 v[22:23], v[22:23], v[134:135], v[224:225]
	v_pk_fma_f32 v[80:81], v[80:81], v[128:129], v[226:227]
	v_pk_fma_f32 v[82:83], v[82:83], v[130:131], v[228:229]
	v_pk_fma_f32 v[16:17], v[16:17], v[132:133], v[230:231]
	v_pk_fma_f32 v[18:19], v[18:19], v[134:135], v[232:233]
	global_store_dwordx4 v156, v[84:87], s[26:27]
	global_store_dwordx4 v156, v[20:23], s[26:27] offset:512
	global_store_dwordx4 v157, v[80:83], s[26:27]
	global_store_dwordx4 v157, v[16:19], s[26:27] offset:512
	s_add_u32 s26, s26, 0x10000
	s_addc_u32 s27, s27, 0
	ds_write_b128 v154, v[68:71]
	ds_write_b128 v154, v[64:67] offset:16
	ds_read_b128 v[68:71], v155
	ds_read_b128 v[64:67], v155 offset:1152
	ds_write_b128 v154, v[4:7]
	ds_write_b128 v154, v[0:3] offset:16
	ds_read_b128 v[4:7], v155
	ds_read_b128 v[0:3], v155 offset:1152
	s_waitcnt vmcnt(12) lgkmcnt(8)
	v_pk_fma_f32 v[76:77], v[76:77], v[128:129], v[180:181]
	v_pk_fma_f32 v[78:79], v[78:79], v[130:131], v[182:183]
	v_pk_fma_f32 v[12:13], v[12:13], v[132:133], v[184:185]
	v_pk_fma_f32 v[14:15], v[14:15], v[134:135], v[186:187]
	v_pk_fma_f32 v[72:73], v[72:73], v[128:129], v[188:189]
	v_pk_fma_f32 v[74:75], v[74:75], v[130:131], v[190:191]
	v_pk_fma_f32 v[8:9], v[8:9], v[132:133], v[192:193]
	v_pk_fma_f32 v[10:11], v[10:11], v[134:135], v[194:195]
	global_store_dwordx4 v156, v[76:79], s[26:27]
	global_store_dwordx4 v156, v[12:15], s[26:27] offset:512
	global_store_dwordx4 v157, v[72:75], s[26:27]
	global_store_dwordx4 v157, v[8:11], s[26:27] offset:512
	s_add_u32 s26, s26, 0x10000
	s_addc_u32 s27, s27, 0
	s_waitcnt vmcnt(8) lgkmcnt(0)
	v_pk_fma_f32 v[68:69], v[68:69], v[128:129], v[196:197]
	v_pk_fma_f32 v[70:71], v[70:71], v[130:131], v[198:199]
	v_pk_fma_f32 v[4:5], v[4:5], v[132:133], v[200:201]
	v_pk_fma_f32 v[6:7], v[6:7], v[134:135], v[202:203]
	v_pk_fma_f32 v[64:65], v[64:65], v[128:129], v[204:205]
	v_pk_fma_f32 v[66:67], v[66:67], v[130:131], v[206:207]
	v_pk_fma_f32 v[0:1], v[0:1], v[132:133], v[214:215]
	v_pk_fma_f32 v[2:3], v[2:3], v[134:135], v[216:217]
	global_store_dwordx4 v156, v[68:71], s[26:27]
	global_store_dwordx4 v156, v[4:7], s[26:27] offset:512
	global_store_dwordx4 v157, v[64:67], s[26:27]
	global_store_dwordx4 v157, v[0:3], s[26:27] offset:512
	s_nop 0
	s_mov_b64 s[26:27], -1
	s_and_b64 vcc, exec, s[4:5]
	s_cbranch_vccnz .LBB0_685
	s_andn2_b64 vcc, exec, s[60:61]
	s_cbranch_vccnz .LBB0_684
	s_barrier
	s_branch .LBB0_684

; DI unsigned pk2(float lo, float hi) { f32x2 v = {lo, hi}; bf16x2_t b = __builtin_convertvector(v, bf16x2_t); return __builtin_bit_cast(unsigned, b); }
;     DI void operator()(const f32x4 (&acc)[2][2][4][2], const Unit& u, int wr, int wc, int fr, int fq) const {
;         const int row0 = u.pm * BM + wr * 64 + fr, col0 = u.pn * BM + wc * 32 + 8 * fq;
; #pragma unroll
;         for (int ai = 0; ai < 2; ++ai)
; #pragma unroll
;             for (int m = 0; m < 4; ++m) { bf16_t* rowp = O + (size_t)(row0 + ai * HALF + m * 16) * ldc + col0;
; #pragma unroll
;                 for (int bj = 0; bj < 2; ++bj) { f32x4 v0 = acc[ai][bj][m][0], v1 = acc[ai][bj][m][1];
;                     if (act) {
; #pragma unroll
;                         for (int q = 0; q < 4; ++q) { float a = fmaxf(v0[q], 0.f), b = fmaxf(v1[q], 0.f); v0[q] = a * a; v1[q] = b * b; } }
;                     u32x4 w; w.x = pk2(v0[0], v0[1]); w.y = pk2(v0[2], v0[3]); w.z = pk2(v1[0], v1[1]); w.w = pk2(v1[2], v1[3]);
;                     *(u32x4*)(rowp + bj * HALF) = w; } }
;     }
.LBB0_764:
	v_and_b32_e32 v192, 15, v142
	v_bfe_u32 v193, v152, 3, 2
	v_lshl_add_u32 v192, v193, 4, v192
	v_lshrrev_b32_e32 v193, 4, v192
	v_and_b32_e32 v194, 3, v192
	v_lshl_add_u32 v193, v193, 2, v194
	v_bfe_u32 v194, v192, 2, 2
	v_lshl_add_u32 v195, v194, 4, v193
	v_lshlrev_b32_e32 v195, 2, v195
	v_and_b32_e32 v196, 0xfffffff0, v142
	v_add_u32_e32 v196, v196, v193
	v_lshl_add_u32 v196, s84, 8, v196
	v_and_b32_e32 v197, 0xffffffe0, v152
	v_lshl_add_u32 v197, v194, 3, v197
	v_lshl_add_u32 v197, s85, 8, v197
	v_mul_lo_u32 v196, v196, s70
	v_add_lshl_u32 v196, v196, v197, 1
	s_lshl_b32 s26, s70, 5
	s_mul_i32 s27, s26, 5
	s_and_b64 vcc, exec, s[46:47]
	s_cbranch_vccz .Lepistore_noact
	v_max_f32_e32 v120, 0, v120
	v_max_f32_e32 v121, 0, v121
	v_max_f32_e32 v122, 0, v122
	v_max_f32_e32 v123, 0, v123
	v_max_f32_e32 v124, 0, v124
	v_max_f32_e32 v125, 0, v125
	v_max_f32_e32 v126, 0, v126
	v_max_f32_e32 v127, 0, v127
	v_pk_mul_f32 v[120:121], v[120:121], v[120:121]
	v_pk_mul_f32 v[122:123], v[122:123], v[122:123]
	v_pk_mul_f32 v[124:125], v[124:125], v[124:125]
	v_pk_mul_f32 v[126:127], v[126:127], v[126:127]
	v_cvt_pk_bf16_f32 v120, v120, v121
	v_cvt_pk_bf16_f32 v121, v122, v123
	v_cvt_pk_bf16_f32 v122, v124, v125
	v_cvt_pk_bf16_f32 v123, v126, v127
	ds_bpermute_b32 v176, v195, v120
	ds_bpermute_b32 v177, v195, v121
	ds_bpermute_b32 v178, v195, v122
	ds_bpermute_b32 v179, v195, v123
	v_max_f32_e32 v116, 0, v116
	v_max_f32_e32 v117, 0, v117
	v_max_f32_e32 v118, 0, v118
	v_max_f32_e32 v119, 0, v119
	v_max_f32_e32 v112, 0, v112
	v_max_f32_e32 v113, 0, v113
	v_max_f32_e32 v114, 0, v114
	v_max_f32_e32 v115, 0, v115
	v_pk_mul_f32 v[116:117], v[116:117], v[116:117]
	v_pk_mul_f32 v[118:119], v[118:119], v[118:119]
	v_pk_mul_f32 v[112:113], v[112:113], v[112:113]
	v_pk_mul_f32 v[114:115], v[114:115], v[114:115]
	v_cvt_pk_bf16_f32 v116, v116, v117
	v_cvt_pk_bf16_f32 v117, v118, v119
	v_cvt_pk_bf16_f32 v118, v112, v113
	v_cvt_pk_bf16_f32 v119, v114, v115
	ds_bpermute_b32 v180, v195, v116
	ds_bpermute_b32 v181, v195, v117
	ds_bpermute_b32 v182, v195, v118
	ds_bpermute_b32 v183, v195, v119
	v_max_f32_e32 v108, 0, v108
	v_max_f32_e32 v109, 0, v109
	v_max_f32_e32 v110, 0, v110
	v_max_f32_e32 v111, 0, v111
	v_max_f32_e32 v104, 0, v104
	v_max_f32_e32 v105, 0, v105
	v_max_f32_e32 v106, 0, v106
	v_max_f32_e32 v107, 0, v107
	v_pk_mul_f32 v[108:109], v[108:109], v[108:109]
	v_pk_mul_f32 v[110:111], v[110:111], v[110:111]
	v_pk_mul_f32 v[104:105], v[104:105], v[104:105]
	v_pk_mul_f32 v[106:107], v[106:107], v[106:107]
	v_cvt_pk_bf16_f32 v108, v108, v109
	v_cvt_pk_bf16_f32 v109, v110, v111
	v_cvt_pk_bf16_f32 v110, v104, v105
	v_cvt_pk_bf16_f32 v111, v106, v107
	s_waitcnt lgkmcnt(4)
	global_store_dwordx4 v196, v[176:179], s[44:45]
	ds_bpermute_b32 v184, v195, v108
	ds_bpermute_b32 v185, v195, v109
	ds_bpermute_b32 v186, v195, v110
	ds_bpermute_b32 v187, v195, v111
	v_max_f32_e32 v100, 0, v100
	v_max_f32_e32 v101, 0, v101
	v_max_f32_e32 v102, 0, v102
	v_max_f32_e32 v103, 0, v103
	v_max_f32_e32 v96, 0, v96
	v_max_f32_e32 v97, 0, v97
	v_max_f32_e32 v98, 0, v98
	v_max_f32_e32 v99, 0, v99
	v_pk_mul_f32 v[100:101], v[100:101], v[100:101]
	v_pk_mul_f32 v[102:103], v[102:103], v[102:103]
	v_pk_mul_f32 v[96:97], v[96:97], v[96:97]
	v_pk_mul_f32 v[98:99], v[98:99], v[98:99]
	v_cvt_pk_bf16_f32 v100, v100, v101
	v_cvt_pk_bf16_f32 v101, v102, v103
	v_cvt_pk_bf16_f32 v102, v96, v97
	v_cvt_pk_bf16_f32 v103, v98, v99
	s_waitcnt lgkmcnt(4)
	global_store_dwordx4 v196, v[180:183], s[44:45] offset:256
	v_add_u32_e32 v196, s26, v196
	ds_bpermute_b32 v188, v195, v100
	ds_bpermute_b32 v189, v195, v101
	ds_bpermute_b32 v190, v195, v102
	ds_bpermute_b32 v191, v195, v103
	v_max_f32_e32 v92, 0, v92
	v_max_f32_e32 v93, 0, v93
	v_max_f32_e32 v94, 0, v94
	v_max_f32_e32 v95, 0, v95
	v_max_f32_e32 v88, 0, v88
	v_max_f32_e32 v89, 0, v89
	v_max_f32_e32 v90, 0, v90
	v_max_f32_e32 v91, 0, v91
	v_pk_mul_f32 v[92:93], v[92:93], v[92:93]
	v_pk_mul_f32 v[94:95], v[94:95], v[94:95]
	v_pk_mul_f32 v[88:89], v[88:89], v[88:89]
	v_pk_mul_f32 v[90:91], v[90:91], v[90:91]
	v_cvt_pk_bf16_f32 v92, v92, v93
	v_cvt_pk_bf16_f32 v93, v94, v95
	v_cvt_pk_bf16_f32 v94, v88, v89
	v_cvt_pk_bf16_f32 v95, v90, v91
	s_waitcnt lgkmcnt(4)
	global_store_dwordx4 v196, v[184:187], s[44:45]
	ds_bpermute_b32 v176, v195, v92
	ds_bpermute_b32 v177, v195, v93
	ds_bpermute_b32 v178, v195, v94
	ds_bpermute_b32 v179, v195, v95
	v_max_f32_e32 v84, 0, v84
	v_max_f32_e32 v85, 0, v85
	v_max_f32_e32 v86, 0, v86
	v_max_f32_e32 v87, 0, v87
	v_max_f32_e32 v80, 0, v80
	v_max_f32_e32 v81, 0, v81
	v_max_f32_e32 v82, 0, v82
	v_max_f32_e32 v83, 0, v83
	v_pk_mul_f32 v[84:85], v[84:85], v[84:85]
	v_pk_mul_f32 v[86:87], v[86:87], v[86:87]
	v_pk_mul_f32 v[80:81], v[80:81], v[80:81]
	v_pk_mul_f32 v[82:83], v[82:83], v[82:83]
	v_cvt_pk_bf16_f32 v84, v84, v85
	v_cvt_pk_bf16_f32 v85, v86, v87
	v_cvt_pk_bf16_f32 v86, v80, v81
	v_cvt_pk_bf16_f32 v87, v82, v83
	s_waitcnt lgkmcnt(4)
	global_store_dwordx4 v196, v[188:191], s[44:45] offset:256
	v_add_u32_e32 v196, s26, v196
	ds_bpermute_b32 v180, v195, v84
	ds_bpermute_b32 v181, v195, v85
	ds_bpermute_b32 v182, v195, v86
	ds_bpermute_b32 v183, v195, v87
	v_max_f32_e32 v76, 0, v76
	v_max_f32_e32 v77, 0, v77
	v_max_f32_e32 v78, 0, v78
	v_max_f32_e32 v79, 0, v79
	v_max_f32_e32 v72, 0, v72
	v_max_f32_e32 v73, 0, v73
	v_max_f32_e32 v74, 0, v74
	v_max_f32_e32 v75, 0, v75
	v_pk_mul_f32 v[76:77], v[76:77], v[76:77]
	v_pk_mul_f32 v[78:79], v[78:79], v[78:79]
	v_pk_mul_f32 v[72:73], v[72:73], v[72:73]
	v_pk_mul_f32 v[74:75], v[74:75], v[74:75]
	v_cvt_pk_bf16_f32 v76, v76, v77
	v_cvt_pk_bf16_f32 v77, v78, v79
	v_cvt_pk_bf16_f32 v78, v72, v73
	v_cvt_pk_bf16_f32 v79, v74, v75
	s_waitcnt lgkmcnt(4)
; DI unsigned pk2(float lo, float hi) { f32x2 v = {lo, hi}; bf16x2_t b = __builtin_convertvector(v, bf16x2_t); return __builtin_bit_cast(unsigned, b); }
;     DI void operator()(const f32x4 (&acc)[2][2][4][2], const Unit& u, int wr, int wc, int fr, int fq) const {
;         const int row0 = u.pm * BM + wr * 64 + fr, col0 = u.pn * BM + wc * 32 + 8 * fq;
; #pragma unroll
;         for (int ai = 0; ai < 2; ++ai)
; #pragma unroll
;             for (int m = 0; m < 4; ++m) { bf16_t* rowp = O + (size_t)(row0 + ai * HALF + m * 16) * ldc + col0;
; #pragma unroll
;                 for (int bj = 0; bj < 2; ++bj) { f32x4 v0 = acc[ai][bj][m][0], v1 = acc[ai][bj][m][1];
;                     if (act) {
; #pragma unroll
;                         for (int q = 0; q < 4; ++q) { float a = fmaxf(v0[q], 0.f), b = fmaxf(v1[q], 0.f); v0[q] = a * a; v1[q] = b * b; } }
;                     u32x4 w; w.x = pk2(v0[0], v0[1]); w.y = pk2(v0[2], v0[3]); w.z = pk2(v1[0], v1[1]); w.w = pk2(v1[2], v1[3]);
;                     *(u32x4*)(rowp + bj * HALF) = w; } }
;     }
	global_store_dwordx4 v196, v[176:179], s[44:45]
	ds_bpermute_b32 v184, v195, v76
	ds_bpermute_b32 v185, v195, v77
	ds_bpermute_b32 v186, v195, v78
	ds_bpermute_b32 v187, v195, v79
	v_max_f32_e32 v68, 0, v68
	v_max_f32_e32 v69, 0, v69
	v_max_f32_e32 v70, 0, v70
	v_max_f32_e32 v71, 0, v71
	v_max_f32_e32 v64, 0, v64
	v_max_f32_e32 v65, 0, v65
	v_max_f32_e32 v66, 0, v66
	v_max_f32_e32 v67, 0, v67
	v_pk_mul_f32 v[68:69], v[68:69], v[68:69]
	v_pk_mul_f32 v[70:71], v[70:71], v[70:71]
	v_pk_mul_f32 v[64:65], v[64:65], v[64:65]
	v_pk_mul_f32 v[66:67], v[66:67], v[66:67]
	v_cvt_pk_bf16_f32 v68, v68, v69
	v_cvt_pk_bf16_f32 v69, v70, v71
	v_cvt_pk_bf16_f32 v70, v64, v65
	v_cvt_pk_bf16_f32 v71, v66, v67
	s_waitcnt lgkmcnt(4)
	global_store_dwordx4 v196, v[180:183], s[44:45] offset:256
	v_add_u32_e32 v196, s26, v196
	ds_bpermute_b32 v188, v195, v68
	ds_bpermute_b32 v189, v195, v69
	ds_bpermute_b32 v190, v195, v70
	ds_bpermute_b32 v191, v195, v71
	v_max_f32_e32 v60, 0, v60
	v_max_f32_e32 v61, 0, v61
	v_max_f32_e32 v62, 0, v62
	v_max_f32_e32 v63, 0, v63
	v_max_f32_e32 v56, 0, v56
	v_max_f32_e32 v57, 0, v57
	v_max_f32_e32 v58, 0, v58
	v_max_f32_e32 v59, 0, v59
	v_pk_mul_f32 v[60:61], v[60:61], v[60:61]
	v_pk_mul_f32 v[62:63], v[62:63], v[62:63]
	v_pk_mul_f32 v[56:57], v[56:57], v[56:57]
	v_pk_mul_f32 v[58:59], v[58:59], v[58:59]
	v_cvt_pk_bf16_f32 v60, v60, v61
	v_cvt_pk_bf16_f32 v61, v62, v63
	v_cvt_pk_bf16_f32 v62, v56, v57
	v_cvt_pk_bf16_f32 v63, v58, v59
	s_waitcnt lgkmcnt(4)
	global_store_dwordx4 v196, v[184:187], s[44:45]
	ds_bpermute_b32 v176, v195, v60
	ds_bpermute_b32 v177, v195, v61
	ds_bpermute_b32 v178, v195, v62
	ds_bpermute_b32 v179, v195, v63
	v_max_f32_e32 v52, 0, v52
	v_max_f32_e32 v53, 0, v53
	v_max_f32_e32 v54, 0, v54
	v_max_f32_e32 v55, 0, v55
	v_max_f32_e32 v48, 0, v48
	v_max_f32_e32 v49, 0, v49
	v_max_f32_e32 v50, 0, v50
	v_max_f32_e32 v51, 0, v51
	v_pk_mul_f32 v[52:53], v[52:53], v[52:53]
	v_pk_mul_f32 v[54:55], v[54:55], v[54:55]
	v_pk_mul_f32 v[48:49], v[48:49], v[48:49]
	v_pk_mul_f32 v[50:51], v[50:51], v[50:51]
	v_cvt_pk_bf16_f32 v52, v52, v53
	v_cvt_pk_bf16_f32 v53, v54, v55
	v_cvt_pk_bf16_f32 v54, v48, v49
	v_cvt_pk_bf16_f32 v55, v50, v51
	s_waitcnt lgkmcnt(4)
	global_store_dwordx4 v196, v[188:191], s[44:45] offset:256
	v_add_u32_e32 v196, s27, v196
	ds_bpermute_b32 v180, v195, v52
	ds_bpermute_b32 v181, v195, v53
	ds_bpermute_b32 v182, v195, v54
	ds_bpermute_b32 v183, v195, v55
	v_max_f32_e32 v44, 0, v44
	v_max_f32_e32 v45, 0, v45
	v_max_f32_e32 v46, 0, v46
	v_max_f32_e32 v47, 0, v47
	v_max_f32_e32 v40, 0, v40
	v_max_f32_e32 v41, 0, v41
	v_max_f32_e32 v42, 0, v42
	v_max_f32_e32 v43, 0, v43
	v_pk_mul_f32 v[44:45], v[44:45], v[44:45]
	v_pk_mul_f32 v[46:47], v[46:47], v[46:47]
	v_pk_mul_f32 v[40:41], v[40:41], v[40:41]
	v_pk_mul_f32 v[42:43], v[42:43], v[42:43]
	v_cvt_pk_bf16_f32 v44, v44, v45
	v_cvt_pk_bf16_f32 v45, v46, v47
	v_cvt_pk_bf16_f32 v46, v40, v41
	v_cvt_pk_bf16_f32 v47, v42, v43
	s_waitcnt lgkmcnt(4)
	global_store_dwordx4 v196, v[176:179], s[44:45]
	ds_bpermute_b32 v184, v195, v44
	ds_bpermute_b32 v185, v195, v45
	ds_bpermute_b32 v186, v195, v46
	ds_bpermute_b32 v187, v195, v47
	v_max_f32_e32 v36, 0, v36
	v_max_f32_e32 v37, 0, v37
	v_max_f32_e32 v38, 0, v38
	v_max_f32_e32 v39, 0, v39
	v_max_f32_e32 v32, 0, v32
	v_max_f32_e32 v33, 0, v33
	v_max_f32_e32 v34, 0, v34
	v_max_f32_e32 v35, 0, v35
	v_pk_mul_f32 v[36:37], v[36:37], v[36:37]
	v_pk_mul_f32 v[38:39], v[38:39], v[38:39]
	v_pk_mul_f32 v[32:33], v[32:33], v[32:33]
	v_pk_mul_f32 v[34:35], v[34:35], v[34:35]
	v_cvt_pk_bf16_f32 v36, v36, v37
	v_cvt_pk_bf16_f32 v37, v38, v39
	v_cvt_pk_bf16_f32 v38, v32, v33
	v_cvt_pk_bf16_f32 v39, v34, v35
	s_waitcnt lgkmcnt(4)
	global_store_dwordx4 v196, v[180:183], s[44:45] offset:256
	v_add_u32_e32 v196, s26, v196
	ds_bpermute_b32 v188, v195, v36
	ds_bpermute_b32 v189, v195, v37
	ds_bpermute_b32 v190, v195, v38
	ds_bpermute_b32 v191, v195, v39
	v_max_f32_e32 v28, 0, v28
	v_max_f32_e32 v29, 0, v29
	v_max_f32_e32 v30, 0, v30
	v_max_f32_e32 v31, 0, v31
	v_max_f32_e32 v24, 0, v24
	v_max_f32_e32 v25, 0, v25
	v_max_f32_e32 v26, 0, v26
	v_max_f32_e32 v27, 0, v27
	v_pk_mul_f32 v[28:29], v[28:29], v[28:29]
	v_pk_mul_f32 v[30:31], v[30:31], v[30:31]
	v_pk_mul_f32 v[24:25], v[24:25], v[24:25]
	v_pk_mul_f32 v[26:27], v[26:27], v[26:27]
	v_cvt_pk_bf16_f32 v28, v28, v29
	v_cvt_pk_bf16_f32 v29, v30, v31
	v_cvt_pk_bf16_f32 v30, v24, v25
	v_cvt_pk_bf16_f32 v31, v26, v27
	s_waitcnt lgkmcnt(4)
	global_store_dwordx4 v196, v[184:187], s[44:45]
	ds_bpermute_b32 v176, v195, v28
	ds_bpermute_b32 v177, v195, v29
	ds_bpermute_b32 v178, v195, v30
	ds_bpermute_b32 v179, v195, v31
	v_max_f32_e32 v20, 0, v20
	v_max_f32_e32 v21, 0, v21
	v_max_f32_e32 v22, 0, v22
	v_max_f32_e32 v23, 0, v23
	v_max_f32_e32 v16, 0, v16
	v_max_f32_e32 v17, 0, v17
	v_max_f32_e32 v18, 0, v18
	v_max_f32_e32 v19, 0, v19
	v_pk_mul_f32 v[20:21], v[20:21], v[20:21]
	v_pk_mul_f32 v[22:23], v[22:23], v[22:23]
	v_pk_mul_f32 v[16:17], v[16:17], v[16:17]
	v_pk_mul_f32 v[18:19], v[18:19], v[18:19]
	v_cvt_pk_bf16_f32 v20, v20, v21
	v_cvt_pk_bf16_f32 v21, v22, v23
	v_cvt_pk_bf16_f32 v22, v16, v17
	v_cvt_pk_bf16_f32 v23, v18, v19
	s_waitcnt lgkmcnt(4)
	global_store_dwordx4 v196, v[188:191], s[44:45] offset:256
	v_add_u32_e32 v196, s26, v196
	ds_bpermute_b32 v180, v195, v20
	ds_bpermute_b32 v181, v195, v21
	ds_bpermute_b32 v182, v195, v22
	ds_bpermute_b32 v183, v195, v23
	v_max_f32_e32 v12, 0, v12
	v_max_f32_e32 v13, 0, v13
	v_max_f32_e32 v14, 0, v14
	v_max_f32_e32 v15, 0, v15
	v_max_f32_e32 v8, 0, v8
	v_max_f32_e32 v9, 0, v9
	v_max_f32_e32 v10, 0, v10
	v_max_f32_e32 v11, 0, v11
	v_pk_mul_f32 v[12:13], v[12:13], v[12:13]
	v_pk_mul_f32 v[14:15], v[14:15], v[14:15]
	v_pk_mul_f32 v[8:9], v[8:9], v[8:9]
	v_pk_mul_f32 v[10:11], v[10:11], v[10:11]
	v_cvt_pk_bf16_f32 v12, v12, v13
	v_cvt_pk_bf16_f32 v13, v14, v15
	v_cvt_pk_bf16_f32 v14, v8, v9
	v_cvt_pk_bf16_f32 v15, v10, v11
	s_waitcnt lgkmcnt(4)
	global_store_dwordx4 v196, v[176:179], s[44:45]
	ds_bpermute_b32 v184, v195, v12
	ds_bpermute_b32 v185, v195, v13
	ds_bpermute_b32 v186, v195, v14
	ds_bpermute_b32 v187, v195, v15
	v_max_f32_e32 v4, 0, v4
	v_max_f32_e32 v5, 0, v5
	v_max_f32_e32 v6, 0, v6
	v_max_f32_e32 v7, 0, v7
	v_max_f32_e32 v0, 0, v0
	v_max_f32_e32 v1, 0, v1
	v_max_f32_e32 v2, 0, v2
	v_max_f32_e32 v3, 0, v3
	v_pk_mul_f32 v[4:5], v[4:5], v[4:5]
	v_pk_mul_f32 v[6:7], v[6:7], v[6:7]
	v_pk_mul_f32 v[0:1], v[0:1], v[0:1]
	v_pk_mul_f32 v[2:3], v[2:3], v[2:3]
	v_cvt_pk_bf16_f32 v4, v4, v5
	v_cvt_pk_bf16_f32 v5, v6, v7
	v_cvt_pk_bf16_f32 v6, v0, v1
	v_cvt_pk_bf16_f32 v7, v2, v3
	s_waitcnt lgkmcnt(4)
	global_store_dwordx4 v196, v[180:183], s[44:45] offset:256
	v_add_u32_e32 v196, s26, v196
	ds_bpermute_b32 v188, v195, v4
	ds_bpermute_b32 v189, v195, v5
	ds_bpermute_b32 v190, v195, v6
	ds_bpermute_b32 v191, v195, v7
	s_waitcnt lgkmcnt(4)
	global_store_dwordx4 v196, v[184:187], s[44:45]
	s_waitcnt lgkmcnt(0)
	global_store_dwordx4 v196, v[188:191], s[44:45] offset:256
	s_branch .Lepistore_tail
; DI unsigned pk2(float lo, float hi) { f32x2 v = {lo, hi}; bf16x2_t b = __builtin_convertvector(v, bf16x2_t); return __builtin_bit_cast(unsigned, b); }
;     DI void operator()(const f32x4 (&acc)[2][2][4][2], const Unit& u, int wr, int wc, int fr, int fq) const {
;         const int row0 = u.pm * BM + wr * 64 + fr, col0 = u.pn * BM + wc * 32 + 8 * fq;
; #pragma unroll
;         for (int ai = 0; ai < 2; ++ai)
; #pragma unroll
;             for (int m = 0; m < 4; ++m) { bf16_t* rowp = O + (size_t)(row0 + ai * HALF + m * 16) * ldc + col0;
; #pragma unroll
;                 for (int bj = 0; bj < 2; ++bj) { f32x4 v0 = acc[ai][bj][m][0], v1 = acc[ai][bj][m][1];
;                     if (act) {
; #pragma unroll
;                         for (int q = 0; q < 4; ++q) { float a = fmaxf(v0[q], 0.f), b = fmaxf(v1[q], 0.f); v0[q] = a * a; v1[q] = b * b; } }
;                     u32x4 w; w.x = pk2(v0[0], v0[1]); w.y = pk2(v0[2], v0[3]); w.z = pk2(v1[0], v1[1]); w.w = pk2(v1[2], v1[3]);
;                     *(u32x4*)(rowp + bj * HALF) = w; } }
;     }
.Lepistore_noact:
	v_cvt_pk_bf16_f32 v120, v120, v121
	v_cvt_pk_bf16_f32 v121, v122, v123
	v_cvt_pk_bf16_f32 v122, v124, v125
	v_cvt_pk_bf16_f32 v123, v126, v127
	ds_bpermute_b32 v176, v195, v120
	ds_bpermute_b32 v177, v195, v121
	ds_bpermute_b32 v178, v195, v122
	ds_bpermute_b32 v179, v195, v123
	v_cvt_pk_bf16_f32 v116, v116, v117
	v_cvt_pk_bf16_f32 v117, v118, v119
	v_cvt_pk_bf16_f32 v118, v112, v113
	v_cvt_pk_bf16_f32 v119, v114, v115
	ds_bpermute_b32 v180, v195, v116
	ds_bpermute_b32 v181, v195, v117
	ds_bpermute_b32 v182, v195, v118
	ds_bpermute_b32 v183, v195, v119
	v_cvt_pk_bf16_f32 v108, v108, v109
	v_cvt_pk_bf16_f32 v109, v110, v111
	v_cvt_pk_bf16_f32 v110, v104, v105
	v_cvt_pk_bf16_f32 v111, v106, v107
	s_waitcnt lgkmcnt(4)
	global_store_dwordx4 v196, v[176:179], s[44:45]
	ds_bpermute_b32 v184, v195, v108
	ds_bpermute_b32 v185, v195, v109
	ds_bpermute_b32 v186, v195, v110
	ds_bpermute_b32 v187, v195, v111
	v_cvt_pk_bf16_f32 v100, v100, v101
	v_cvt_pk_bf16_f32 v101, v102, v103
	v_cvt_pk_bf16_f32 v102, v96, v97
	v_cvt_pk_bf16_f32 v103, v98, v99
	s_waitcnt lgkmcnt(4)
	global_store_dwordx4 v196, v[180:183], s[44:45] offset:256
	v_add_u32_e32 v196, s26, v196
	ds_bpermute_b32 v188, v195, v100
	ds_bpermute_b32 v189, v195, v101
	ds_bpermute_b32 v190, v195, v102
	ds_bpermute_b32 v191, v195, v103
	v_cvt_pk_bf16_f32 v92, v92, v93
	v_cvt_pk_bf16_f32 v93, v94, v95
	v_cvt_pk_bf16_f32 v94, v88, v89
	v_cvt_pk_bf16_f32 v95, v90, v91
	s_waitcnt lgkmcnt(4)
	global_store_dwordx4 v196, v[184:187], s[44:45]
	ds_bpermute_b32 v176, v195, v92
	ds_bpermute_b32 v177, v195, v93
	ds_bpermute_b32 v178, v195, v94
	ds_bpermute_b32 v179, v195, v95
	v_cvt_pk_bf16_f32 v84, v84, v85
	v_cvt_pk_bf16_f32 v85, v86, v87
	v_cvt_pk_bf16_f32 v86, v80, v81
	v_cvt_pk_bf16_f32 v87, v82, v83
	s_waitcnt lgkmcnt(4)
	global_store_dwordx4 v196, v[188:191], s[44:45] offset:256
	v_add_u32_e32 v196, s26, v196
	ds_bpermute_b32 v180, v195, v84
	ds_bpermute_b32 v181, v195, v85
	ds_bpermute_b32 v182, v195, v86
	ds_bpermute_b32 v183, v195, v87
	v_cvt_pk_bf16_f32 v76, v76, v77
	v_cvt_pk_bf16_f32 v77, v78, v79
	v_cvt_pk_bf16_f32 v78, v72, v73
	v_cvt_pk_bf16_f32 v79, v74, v75
	s_waitcnt lgkmcnt(4)
	global_store_dwordx4 v196, v[176:179], s[44:45]
	ds_bpermute_b32 v184, v195, v76
	ds_bpermute_b32 v185, v195, v77
	ds_bpermute_b32 v186, v195, v78
	ds_bpermute_b32 v187, v195, v79
	v_cvt_pk_bf16_f32 v68, v68, v69
	v_cvt_pk_bf16_f32 v69, v70, v71
	v_cvt_pk_bf16_f32 v70, v64, v65
	v_cvt_pk_bf16_f32 v71, v66, v67
	s_waitcnt lgkmcnt(4)
	global_store_dwordx4 v196, v[180:183], s[44:45] offset:256
	v_add_u32_e32 v196, s26, v196
	ds_bpermute_b32 v188, v195, v68
	ds_bpermute_b32 v189, v195, v69
	ds_bpermute_b32 v190, v195, v70
	ds_bpermute_b32 v191, v195, v71
	v_cvt_pk_bf16_f32 v60, v60, v61
	v_cvt_pk_bf16_f32 v61, v62, v63
	v_cvt_pk_bf16_f32 v62, v56, v57
	v_cvt_pk_bf16_f32 v63, v58, v59
	s_waitcnt lgkmcnt(4)
	global_store_dwordx4 v196, v[184:187], s[44:45]
	ds_bpermute_b32 v176, v195, v60
	ds_bpermute_b32 v177, v195, v61
	ds_bpermute_b32 v178, v195, v62
	ds_bpermute_b32 v179, v195, v63
	v_cvt_pk_bf16_f32 v52, v52, v53
	v_cvt_pk_bf16_f32 v53, v54, v55
	v_cvt_pk_bf16_f32 v54, v48, v49
	v_cvt_pk_bf16_f32 v55, v50, v51
	s_waitcnt lgkmcnt(4)
	global_store_dwordx4 v196, v[188:191], s[44:45] offset:256
	v_add_u32_e32 v196, s27, v196
	ds_bpermute_b32 v180, v195, v52
	ds_bpermute_b32 v181, v195, v53
	ds_bpermute_b32 v182, v195, v54
	ds_bpermute_b32 v183, v195, v55
	v_cvt_pk_bf16_f32 v44, v44, v45
	v_cvt_pk_bf16_f32 v45, v46, v47
	v_cvt_pk_bf16_f32 v46, v40, v41
	v_cvt_pk_bf16_f32 v47, v42, v43
	s_waitcnt lgkmcnt(4)
	global_store_dwordx4 v196, v[176:179], s[44:45]
	ds_bpermute_b32 v184, v195, v44
	ds_bpermute_b32 v185, v195, v45
	ds_bpermute_b32 v186, v195, v46
	ds_bpermute_b32 v187, v195, v47
	v_cvt_pk_bf16_f32 v36, v36, v37
	v_cvt_pk_bf16_f32 v37, v38, v39
	v_cvt_pk_bf16_f32 v38, v32, v33
	v_cvt_pk_bf16_f32 v39, v34, v35
	s_waitcnt lgkmcnt(4)
	global_store_dwordx4 v196, v[180:183], s[44:45] offset:256
	v_add_u32_e32 v196, s26, v196
	ds_bpermute_b32 v188, v195, v36
	ds_bpermute_b32 v189, v195, v37
	ds_bpermute_b32 v190, v195, v38
	ds_bpermute_b32 v191, v195, v39
	v_cvt_pk_bf16_f32 v28, v28, v29
	v_cvt_pk_bf16_f32 v29, v30, v31
	v_cvt_pk_bf16_f32 v30, v24, v25
	v_cvt_pk_bf16_f32 v31, v26, v27
	s_waitcnt lgkmcnt(4)
	global_store_dwordx4 v196, v[184:187], s[44:45]
	ds_bpermute_b32 v176, v195, v28
	ds_bpermute_b32 v177, v195, v29
	ds_bpermute_b32 v178, v195, v30
	ds_bpermute_b32 v179, v195, v31
	v_cvt_pk_bf16_f32 v20, v20, v21
	v_cvt_pk_bf16_f32 v21, v22, v23
	v_cvt_pk_bf16_f32 v22, v16, v17
	v_cvt_pk_bf16_f32 v23, v18, v19
	s_waitcnt lgkmcnt(4)
	global_store_dwordx4 v196, v[188:191], s[44:45] offset:256
	v_add_u32_e32 v196, s26, v196
	ds_bpermute_b32 v180, v195, v20
	ds_bpermute_b32 v181, v195, v21
	ds_bpermute_b32 v182, v195, v22
	ds_bpermute_b32 v183, v195, v23
	v_cvt_pk_bf16_f32 v12, v12, v13
	v_cvt_pk_bf16_f32 v13, v14, v15
	v_cvt_pk_bf16_f32 v14, v8, v9
	v_cvt_pk_bf16_f32 v15, v10, v11
	s_waitcnt lgkmcnt(4)
	global_store_dwordx4 v196, v[176:179], s[44:45]
	ds_bpermute_b32 v184, v195, v12
	ds_bpermute_b32 v185, v195, v13
	ds_bpermute_b32 v186, v195, v14
	ds_bpermute_b32 v187, v195, v15
	v_cvt_pk_bf16_f32 v4, v4, v5
	v_cvt_pk_bf16_f32 v5, v6, v7
	v_cvt_pk_bf16_f32 v6, v0, v1
	v_cvt_pk_bf16_f32 v7, v2, v3
	s_waitcnt lgkmcnt(4)
	global_store_dwordx4 v196, v[180:183], s[44:45] offset:256
	v_add_u32_e32 v196, s26, v196
	ds_bpermute_b32 v188, v195, v4
	ds_bpermute_b32 v189, v195, v5
	ds_bpermute_b32 v190, v195, v6
	ds_bpermute_b32 v191, v195, v7
	s_waitcnt lgkmcnt(4)
	global_store_dwordx4 v196, v[184:187], s[44:45]
	s_waitcnt lgkmcnt(0)
	global_store_dwordx4 v196, v[188:191], s[44:45] offset:256
.Lepistore_tail:
	s_and_b64 vcc, exec, s[4:5]
	s_mov_b64 s[4:5], -1
	s_cbranch_vccnz .LBB0_748
	s_andn2_b64 vcc, exec, s[8:9]
	s_cbranch_vccnz .LBB0_747
	s_barrier
	s_branch .LBB0_747

; #define LAS __attribute__((address_space(3)))
; __global__ void __launch_bounds__(NTHREADS) fwd_kernel(KArgs a) {
;     extern __shared__ __attribute__((aligned(16))) unsigned char lds_raw[];
;     LAS unsigned char* lds = (LAS unsigned char*)lds_raw;
	.amdhsa_kernel _Z10fwd_kernel5KArgs
		.amdhsa_group_segment_fixed_size 18432
		.amdhsa_private_segment_fixed_size 0
		.amdhsa_kernarg_size 560
		.amdhsa_user_sgpr_count 2
		.amdhsa_user_sgpr_dispatch_ptr 0
		.amdhsa_user_sgpr_queue_ptr 0
		.amdhsa_user_sgpr_kernarg_segment_ptr 1
		.amdhsa_user_sgpr_dispatch_id 0
		.amdhsa_user_sgpr_kernarg_preload_length 0
		.amdhsa_user_sgpr_kernarg_preload_offset 0
		.amdhsa_user_sgpr_private_segment_size 0
		.amdhsa_uses_dynamic_stack 0
		.amdhsa_enable_private_segment 0
		.amdhsa_system_sgpr_workgroup_id_x 1
		.amdhsa_system_sgpr_workgroup_id_y 0
		.amdhsa_system_sgpr_workgroup_id_z 0
		.amdhsa_system_sgpr_workgroup_info 0
		.amdhsa_system_vgpr_workitem_id 2
		.amdhsa_next_free_vgpr 256
		.amdhsa_next_free_sgpr 98
		.amdhsa_accum_offset 256
		.amdhsa_reserve_vcc 1
		.amdhsa_float_round_mode_32 0
		.amdhsa_float_round_mode_16_64 0
		.amdhsa_float_denorm_mode_32 3
		.amdhsa_float_denorm_mode_16_64 3
		.amdhsa_dx10_clamp 1
		.amdhsa_ieee_mode 1
		.amdhsa_fp16_overflow 0
		.amdhsa_tg_split 0
		.amdhsa_exception_fp_ieee_invalid_op 0
		.amdhsa_exception_fp_denorm_src 0
		.amdhsa_exception_fp_ieee_div_zero 0
		.amdhsa_exception_fp_ieee_overflow 0
		.amdhsa_exception_fp_ieee_underflow 0
		.amdhsa_exception_fp_ieee_inexact 0
		.amdhsa_exception_int_div_zero 0
	.end_amdhsa_kernel

; #define LAS __attribute__((address_space(3)))
; __global__ void __launch_bounds__(NTHREADS) fwd_kernel(KArgs a) {
;     extern __shared__ __attribute__((aligned(16))) unsigned char lds_raw[];
;     LAS unsigned char* lds = (LAS unsigned char*)lds_raw;
amdhsa.kernels:
  - .agpr_count:     0
    .args:
      - .offset:         0
        .size:           304
        .value_kind:     by_value
      - .offset:         304
        .size:           4
        .value_kind:     hidden_block_count_x
      - .offset:         308
        .size:           4
        .value_kind:     hidden_block_count_y
      - .offset:         312
        .size:           4
        .value_kind:     hidden_block_count_z
      - .offset:         316
        .size:           2
        .value_kind:     hidden_group_size_x
      - .offset:         318
        .size:           2
        .value_kind:     hidden_group_size_y
      - .offset:         320
        .size:           2
        .value_kind:     hidden_group_size_z
      - .offset:         322
        .size:           2
        .value_kind:     hidden_remainder_x
      - .offset:         324
        .size:           2
        .value_kind:     hidden_remainder_y
      - .offset:         326
        .size:           2
        .value_kind:     hidden_remainder_z
      - .offset:         344
        .size:           8
        .value_kind:     hidden_global_offset_x
      - .offset:         352
        .size:           8
        .value_kind:     hidden_global_offset_y
      - .offset:         360
        .size:           8
        .value_kind:     hidden_global_offset_z
      - .offset:         368
        .size:           2
        .value_kind:     hidden_grid_dims
      - .offset:         392
        .size:           8
        .value_kind:     hidden_multigrid_sync_arg
      - .offset:         424
        .size:           4
        .value_kind:     hidden_dynamic_lds_size
    .group_segment_fixed_size: 18432
    .kernarg_segment_align: 8
    .kernarg_segment_size: 560
    .language:       OpenCL C
    .language_version:
      - 2
      - 0
    .max_flat_workgroup_size: 512
    .name:           _Z10fwd_kernel5KArgs
    .private_segment_fixed_size: 0
    .sgpr_count:     104
    .sgpr_spill_count: 188
    .symbol:         _Z10fwd_kernel5KArgs.kd
    .uniform_work_group_size: 1
    .uses_dynamic_stack: false
    .vgpr_count:     256
    .vgpr_spill_count: 0
    .wavefront_size: 64
